# one static s_setprio 1 at entry for waves 4-7 (younger half), on top of the previous version
# speedup vs baseline: 1.0077x; 1.0063x over previous
; #define LAS __attribute__((address_space(3)))
; __device__ __forceinline__ unsigned xb_add(unsigned* p, unsigned v) { return __hip_atomic_fetch_add(p, v, __ATOMIC_RELAXED, __HIP_MEMORY_SCOPE_AGENT); }
; __device__ __forceinline__ unsigned xb_xcc_id() { return (unsigned)__builtin_amdgcn_s_getreg((3 << 11) | 20) & 0xFu; }
; __device__ __forceinline__ XcdBarrier xcd_barrier_post(unsigned* bar, volatile LAS unsigned* st) {
;     XcdBarrier b; b.bar = bar; b.x = xb_xcc_id(); b.st = st;
;     if (threadIdx.x == 0) (void)xb_add(&bar[XB_XCNT(b.x)], 1u);
;     return b;
; __global__ void __launch_bounds__(NTHR, 2) fwd_kernel(Args args) {
;     extern __shared__ __attribute__((aligned(16))) unsigned char lds_raw[];
;     Frame F;
;     F.lds = (ldsp)lds_raw; F.MISC = (volatile LAS unsigned*)(F.lds + MISC_OFF);
;     F.tid = threadIdx.x; F.lane = F.tid & 63; F.wave = __builtin_amdgcn_readfirstlane(F.tid >> 6); F.G = gridDim.x; F.bid = blockIdx.x;
;     F.out = args.out; unsigned char* ws = args.ws; F.ws = ws;
;     for (int u = F.tid; u < (LDS_BYTES - MISC_OFF) / 4; u += NTHR) ((LAS unsigned*)(F.lds + MISC_OFF))[u] = 0u;
;     __syncthreads();
;     const int lo = args.ph_lo, hi = args.ph_hi;
;     XcdBarrier bar; bar.bar = (unsigned*)(ws + WS_CTL) + CW_BAR; bar.x = 0; bar.st = nullptr;
;     if (hi - lo > 1) bar = xcd_barrier_post((unsigned*)(ws + WS_CTL) + CW_BAR, F.MISC + 8);
_Z10fwd_kernel4Args:
	v_readfirstlane_b32 s101, v0
	s_lshr_b32 s101, s101, 6
	s_cmp_ge_u32 s101, 4
	s_cbranch_scc0 .Lprio_done
	s_setprio 1
.Lprio_done:
	s_mov_b32 s60, s2
	s_load_dwordx4 s[76:79], s[0:1], 0xb0
	s_load_dwordx2 s[2:3], s[0:1], 0xc0
	v_cmp_gt_u32_e32 vcc, 64, v0
	s_waitcnt lgkmcnt(0)
	v_writelane_b32 v252, s2, 0
	s_nop 1
	v_writelane_b32 v252, s3, 1
	s_add_u32 s2, s0, 0xc8
	v_writelane_b32 v252, s0, 2
	s_addc_u32 s3, s1, 0
	s_nop 0
	v_writelane_b32 v252, s1, 3
	v_writelane_b32 v252, s2, 4
	s_nop 1
	v_writelane_b32 v252, s3, 5
	s_and_saveexec_b64 s[0:1], vcc
	v_lshl_add_u32 v1, v0, 2, 0
	v_add_u32_e32 v1, 0x27000, v1
	v_mov_b32_e32 v2, 0
	ds_write_b32 v1, v2
	s_or_b64 exec, exec, s[0:1]
	v_readlane_b32 s0, v252, 2
	v_readlane_b32 s1, v252, 3
	s_load_dword s50, s[0:1], 0xc8
	v_readlane_b32 s0, v252, 0
	s_add_u32 s2, s78, 0x4000
	v_readlane_b32 s1, v252, 1
	s_addc_u32 s3, s79, 0
	s_sub_i32 s0, s1, s0
	v_writelane_b32 v252, s0, 6
	s_cmp_lt_i32 s0, 2
	s_mov_b32 s0, 0
	v_writelane_b32 v252, s0, 7
	s_mov_b32 s6, 0
	v_cmp_eq_u32_e32 vcc, 0, v0
	v_writelane_b32 v252, s0, 8
	s_waitcnt lgkmcnt(0)
	s_barrier
	s_cbranch_scc1 .LBB0_7
	s_getreg_b32 s0, hwreg(HW_REG_XCC_ID, 0, 4)
	s_and_b32 s0, s0, 15
	v_writelane_b32 v252, s0, 7
	s_and_saveexec_b64 s[0:1], vcc
	s_cbranch_execz .LBB0_6
	s_mov_b64 s[4:5], exec
	v_mbcnt_lo_u32_b32 v1, s4, 0
	v_mbcnt_hi_u32_b32 v1, s5, v1
	v_cmp_eq_u32_e32 vcc, 0, v1
	s_and_b64 s[8:9], exec, vcc
	s_mov_b64 exec, s[8:9]
	s_cbranch_execz .LBB0_6
	v_readlane_b32 s7, v252, 7
	s_lshl_b32 s7, s7, 8
	s_bcnt1_i32_b64 s4, s[4:5]
	v_mov_b32_e32 v1, s7
	v_mov_b32_e32 v2, s4
	global_atomic_add v1, v2, s[2:3] offset:1024
